# v10 + EpiQK: hoist the eight per-row-group ss loads to the epilogue start (one wait instead of eight)
# speedup vs baseline: 1.0067x; 1.0067x over previous
; __device__ __forceinline__ float rs_from_ss(float ss) { return __builtin_amdgcn_rsqf(ss * (1.0f / 1024.0f) + RMS_EPS); }
;     __device__ __forceinline__ void operator()(const f32x4 (&acc)[2][2][4][2], const Unit& u, int wr, int wc, int fr, int fq) const {
;     ...
;             for (int n = 0; n < 2; ++n) g[bj][n] = *(const f32x4*)(gp + 32 * bj + 8 * fq + 4 * n) * gs;
; #pragma unroll
;         for (int ai = 0; ai < 2; ++ai)
; #pragma unroll
;             for (int m = 0; m < 4; ++m) { const int row = row0 + ai * HALF + m * 16; const float rs = rs_from_ss(ss[row]); f32x4 v[2][2]; float sq = 0.f;
; #pragma unroll
;                 for (int bj = 0; bj < 2; ++bj)
; #pragma unroll
;                     for (int n = 0; n < 2; ++n) { v[bj][n] = acc[ai][bj][m][n] * rs; sq += (v[bj][n][0] * v[bj][n][0] + v[bj][n][1] * v[bj][n][1]) + (v[bj][n][2] * v[bj][n][2] + v[bj][n][3] * v[bj][n][3]); }
;                 sq += __shfl_xor(sq, 16); sq += __shfl_xor(sq, 32);
;                 const float rn = __builtin_amdgcn_rsqf(sq * (1.0f / 64.0f) + RMS_EPS);
;                 float* kd = nullptr;
;                 if (isK) { if (row < NP) { const int pos = row & 16383, b = row >> 14; if (pos >= 15872) kd = kp + ((size_t)(b * 512 + pos - 15872)) * 1024 + head * 64 + 8 * fq; }
;                            else kd = ks + (size_t)(row - NP) * 1024 + head * 64 + 8 * fq; }
.LBB0_311:
	s_lshl_b32 s24, s22, 8
	s_add_i32 s24, s24, s60
	v_or_b32_e32 v164, s24, v1
	v_ashrrev_i32_e32 v165, 31, v164
	v_lshl_add_u64 v[166:167], v[164:165], 2, s[4:5]
	global_load_dword v161, v[166:167], off
	global_load_dword v210, v[166:167], off offset:64
	global_load_dword v211, v[166:167], off offset:128
	global_load_dword v212, v[166:167], off offset:192
	global_load_dword v213, v[166:167], off offset:512
	global_load_dword v214, v[166:167], off offset:576
	global_load_dword v215, v[166:167], off offset:640
	global_load_dword v216, v[166:167], off offset:704
	s_lshl_b32 s3, s2, 2
	s_and_b32 s3, s3, 12
	s_cmp_gt_i32 s2, 3
	s_cselect_b64 s[22:23], -1, 0
	s_and_b64 s[26:27], s[22:23], exec
	s_cselect_b32 s26, s50, s48
	s_cselect_b32 s27, s51, s49
	global_load_dwordx4 v[138:141], v160, s[26:27] offset:16
	global_load_dwordx4 v[142:145], v160, s[26:27]
	global_load_dwordx4 v[130:133], v160, s[26:27] offset:144
	global_load_dwordx4 v[134:137], v160, s[26:27] offset:128
	v_and_b32_e32 v165, 64, v233
	v_xor_b32_e32 v163, 16, v233
	v_add_u32_e32 v176, 64, v165
	v_cmp_lt_i32_e32 vcc, v163, v176
	s_or_b32 s15, s3, s59
	s_ashr_i32 s3, s24, 5
	v_cndmask_b32_e32 v163, v233, v163, vcc
	v_lshlrev_b32_e32 v165, 2, v163
	s_and_b32 s38, s3, 0xfffffe00
	s_lshl_b32 s17, s15, 6
	s_addk_i32 s38, 0xc200
	s_cmp_lt_i32 s2, 4
	s_waitcnt vmcnt(0)
	v_fmamk_f32 v161, v161, 0x3a800000, v232
	v_rsq_f32_e32 v174, v161
	s_nop 0
	v_pk_mul_f32 v[178:179], v[128:129], v[174:175] op_sel_hi:[1,0]
	v_pk_mul_f32 v[180:181], v[126:127], v[174:175] op_sel_hi:[1,0]
	v_pk_mul_f32 v[182:183], v[124:125], v[174:175] op_sel_hi:[1,0]
	v_pk_mul_f32 v[184:185], v[122:123], v[174:175] op_sel_hi:[1,0]
	v_pk_mul_f32 v[168:169], v[120:121], v[174:175] op_sel_hi:[1,0]
	v_pk_mul_f32 v[170:171], v[118:119], v[174:175] op_sel_hi:[1,0]
	v_pk_mul_f32 v[172:173], v[116:117], v[174:175] op_sel_hi:[1,0]
	v_pk_mul_f32 v[174:175], v[114:115], v[174:175] op_sel_hi:[1,0]
	v_mul_f32_e32 v114, v181, v181
	v_mul_f32_e32 v115, v179, v179
	v_mul_f32_e32 v116, v185, v185
	v_mul_f32_e32 v117, v183, v183
	v_mul_f32_e32 v118, v171, v171
	v_mul_f32_e32 v119, v169, v169
	v_fmac_f32_e32 v114, v180, v180
	v_fmac_f32_e32 v115, v178, v178
	v_fmac_f32_e32 v116, v184, v184
	v_fmac_f32_e32 v117, v182, v182
	v_mul_f32_e32 v120, v175, v175
	v_mul_f32_e32 v121, v173, v173
	v_fmac_f32_e32 v118, v170, v170
	v_fmac_f32_e32 v119, v168, v168
	v_add_f32_e32 v114, v114, v115
	v_add_f32_e32 v115, v116, v117
	v_fmac_f32_e32 v120, v174, v174
	v_fmac_f32_e32 v121, v172, v172
	v_add_f32_e32 v116, v118, v119
	v_add_f32_e32 v114, v114, v115
	v_add_f32_e32 v114, v116, v114
	v_add_f32_e32 v115, v120, v121
	v_add_f32_e32 v114, v115, v114
	ds_bpermute_b32 v115, v165, v114
	v_xor_b32_e32 v116, 32, v233
	v_cmp_lt_i32_e32 vcc, v116, v176
	v_mov_b64_e32 v[176:177], 0
	s_waitcnt lgkmcnt(0)
	v_add_f32_e32 v114, v114, v115
	v_cndmask_b32_e32 v116, v233, v116, vcc
	v_lshlrev_b32_e32 v209, 2, v116
	ds_bpermute_b32 v115, v209, v114
	s_cbranch_scc1 .LBB0_317
	s_movk_i32 s2, 0x7fff
	v_cmp_lt_i32_e32 vcc, s2, v164
	s_and_saveexec_b64 s[2:3], vcc
	s_xor_b64 s[2:3], exec, s[2:3]
	v_add_u32_e32 v116, 0xffff8000, v164
	v_mov_b32_e32 v117, v0
	v_lshlrev_b64 v[116:117], 12, v[116:117]
	v_lshl_add_u64 v[116:117], s[10:11], 0, v[116:117]
	s_lshl_b32 s72, s17, 2
	v_lshl_add_u64 v[116:117], v[116:117], 0, s[72:73]
	v_mov_b32_e32 v161, v0
	v_lshl_add_u64 v[176:177], v[116:117], 0, v[160:161]
	s_andn2_saveexec_b64 s[2:3], s[2:3]
	s_cbranch_execz .LBB0_316
	v_and_b32_e32 v118, 0x3fcf, v164
	v_add_u32_e32 v116, s38, v118
	v_ashrrev_i32_e32 v117, 31, v116
	v_lshlrev_b64 v[116:117], 12, v[116:117]
	v_lshl_add_u64 v[116:117], s[8:9], 0, v[116:117]
	s_lshl_b32 s72, s17, 2
	v_lshl_add_u64 v[116:117], v[116:117], 0, s[72:73]
	v_mov_b32_e32 v161, v0
	s_movk_i32 s25, 0x3dff
	v_lshl_add_u64 v[116:117], v[116:117], 0, v[160:161]
	v_cmp_lt_u32_e32 vcc, s25, v118
	s_nop 1
	v_cndmask_b32_e32 v177, 0, v117, vcc
	v_cndmask_b32_e32 v176, 0, v116, vcc

; __device__ __forceinline__ float rs_from_ss(float ss) { return __builtin_amdgcn_rsqf(ss * (1.0f / 1024.0f) + RMS_EPS); }
;     __device__ __forceinline__ void operator()(const f32x4 (&acc)[2][2][4][2], const Unit& u, int wr, int wc, int fr, int fq) const {
;     ...
;             for (int m = 0; m < 4; ++m) { const int row = row0 + ai * HALF + m * 16; const float rs = rs_from_ss(ss[row]); f32x4 v[2][2]; float sq = 0.f;
; #pragma unroll
;                 for (int bj = 0; bj < 2; ++bj)
; #pragma unroll
;                     for (int n = 0; n < 2; ++n) { v[bj][n] = acc[ai][bj][m][n] * rs; sq += (v[bj][n][0] * v[bj][n][0] + v[bj][n][1] * v[bj][n][1]) + (v[bj][n][2] * v[bj][n][2] + v[bj][n][3] * v[bj][n][3]); }
;                 sq += __shfl_xor(sq, 16); sq += __shfl_xor(sq, 32);
;                 const float rn = __builtin_amdgcn_rsqf(sq * (1.0f / 64.0f) + RMS_EPS);
;                 float* kd = nullptr;
;                 if (isK) { if (row < NP) { const int pos = row & 16383, b = row >> 14; if (pos >= 15872) kd = kp + ((size_t)(b * 512 + pos - 15872)) * 1024 + head * 64 + 8 * fq; }
;                            else kd = ks + (size_t)(row - NP) * 1024 + head * 64 + 8 * fq; }
.LBB0_321:
	s_or_b64 exec, exec, s[26:27]
	v_or_b32_e32 v114, 16, v164
	v_ashrrev_i32_e32 v115, 31, v114
	v_lshl_add_u64 v[116:117], v[114:115], 2, s[4:5]
	v_mov_b64_e32 v[140:141], 0
	s_andn2_b64 vcc, exec, s[22:23]
	v_fmamk_f32 v115, v210, 0x3a800000, v232
	v_rsq_f32_e32 v138, v115
	s_nop 0
	v_pk_mul_f32 v[112:113], v[112:113], v[138:139] op_sel_hi:[1,0]
	v_pk_mul_f32 v[110:111], v[110:111], v[138:139] op_sel_hi:[1,0]
	v_mul_f32_e32 v116, v113, v113
	v_mul_f32_e32 v115, v111, v111
	v_fmac_f32_e32 v115, v110, v110
	v_fmac_f32_e32 v116, v112, v112
	v_add_f32_e32 v115, v115, v116
	v_pk_mul_f32 v[116:117], v[108:109], v[138:139] op_sel_hi:[1,0]
	v_pk_mul_f32 v[118:119], v[106:107], v[138:139] op_sel_hi:[1,0]
	v_mul_f32_e32 v107, v117, v117
	v_mul_f32_e32 v106, v119, v119
	v_fmac_f32_e32 v106, v118, v118
	v_fmac_f32_e32 v107, v116, v116
	v_add_f32_e32 v106, v106, v107
	v_add_f32_e32 v115, v115, v106
	v_pk_mul_f32 v[106:107], v[104:105], v[138:139] op_sel_hi:[1,0]
	v_pk_mul_f32 v[108:109], v[102:103], v[138:139] op_sel_hi:[1,0]
	v_mul_f32_e32 v103, v107, v107
	v_mul_f32_e32 v102, v109, v109
	v_pk_mul_f32 v[120:121], v[100:101], v[138:139] op_sel_hi:[1,0]
	v_pk_mul_f32 v[138:139], v[98:99], v[138:139] op_sel_hi:[1,0]
	v_fmac_f32_e32 v102, v108, v108
	v_fmac_f32_e32 v103, v106, v106
	v_mul_f32_e32 v98, v139, v139
	v_mul_f32_e32 v99, v121, v121
	v_add_f32_e32 v102, v102, v103
	v_fmac_f32_e32 v98, v138, v138
	v_fmac_f32_e32 v99, v120, v120
	v_add_f32_e32 v102, v102, v115
	v_add_f32_e32 v98, v98, v99
	v_add_f32_e32 v98, v98, v102
	ds_bpermute_b32 v99, v165, v98
	v_cndmask_b32_e64 v100, 0, 1, s[22:23]
	v_cmp_ne_u32_e64 s[46:47], 1, v100
	s_waitcnt lgkmcnt(0)
	v_add_f32_e32 v98, v98, v99
	ds_bpermute_b32 v99, v209, v98
	s_cbranch_vccnz .LBB0_327
	s_movk_i32 s22, 0x7fff
	v_cmp_lt_i32_e32 vcc, s22, v114
	s_and_saveexec_b64 s[22:23], vcc
	s_xor_b64 s[22:23], exec, s[22:23]
	v_add_u32_e32 v100, 0xffff8010, v164
	v_mov_b32_e32 v101, v0
	v_lshlrev_b64 v[100:101], 12, v[100:101]
	v_lshl_add_u64 v[100:101], s[10:11], 0, v[100:101]
	s_lshl_b32 s72, s17, 2
	v_lshl_add_u64 v[100:101], v[100:101], 0, s[72:73]
	v_mov_b32_e32 v161, v0
	v_lshl_add_u64 v[140:141], v[100:101], 0, v[160:161]
	s_andn2_saveexec_b64 s[22:23], s[22:23]
	s_cbranch_execz .LBB0_326
	v_and_b32_e32 v102, 0x3fdf, v114
	v_add_u32_e32 v100, s38, v102
	v_ashrrev_i32_e32 v101, 31, v100
	v_lshlrev_b64 v[100:101], 12, v[100:101]
	v_lshl_add_u64 v[100:101], s[8:9], 0, v[100:101]
	s_lshl_b32 s72, s17, 2
	v_lshl_add_u64 v[100:101], v[100:101], 0, s[72:73]
	v_mov_b32_e32 v161, v0
	s_movk_i32 s26, 0x3dff
	v_lshl_add_u64 v[100:101], v[100:101], 0, v[160:161]
	v_cmp_lt_u32_e32 vcc, s26, v102
	s_nop 1
	v_cndmask_b32_e32 v141, 0, v101, vcc
	v_cndmask_b32_e32 v140, 0, v100, vcc

; __device__ __forceinline__ float rs_from_ss(float ss) { return __builtin_amdgcn_rsqf(ss * (1.0f / 1024.0f) + RMS_EPS); }
;     __device__ __forceinline__ void operator()(const f32x4 (&acc)[2][2][4][2], const Unit& u, int wr, int wc, int fr, int fq) const {
;     ...
;             for (int m = 0; m < 4; ++m) { const int row = row0 + ai * HALF + m * 16; const float rs = rs_from_ss(ss[row]); f32x4 v[2][2]; float sq = 0.f;
; #pragma unroll
;                 for (int bj = 0; bj < 2; ++bj)
; #pragma unroll
;                     for (int n = 0; n < 2; ++n) { v[bj][n] = acc[ai][bj][m][n] * rs; sq += (v[bj][n][0] * v[bj][n][0] + v[bj][n][1] * v[bj][n][1]) + (v[bj][n][2] * v[bj][n][2] + v[bj][n][3] * v[bj][n][3]); }
;                 sq += __shfl_xor(sq, 16); sq += __shfl_xor(sq, 32);
;                 const float rn = __builtin_amdgcn_rsqf(sq * (1.0f / 64.0f) + RMS_EPS);
;                 float* kd = nullptr;
;                 if (isK) { if (row < NP) { const int pos = row & 16383, b = row >> 14; if (pos >= 15872) kd = kp + ((size_t)(b * 512 + pos - 15872)) * 1024 + head * 64 + 8 * fq; }
;                            else kd = ks + (size_t)(row - NP) * 1024 + head * 64 + 8 * fq; }
.LBB0_331:
	s_or_b64 exec, exec, s[22:23]
	v_or_b32_e32 v98, 32, v164
	v_ashrrev_i32_e32 v99, 31, v98
	v_lshl_add_u64 v[100:101], v[98:99], 2, s[4:5]
	v_mov_b64_e32 v[108:109], 0
	s_and_b64 vcc, exec, s[46:47]
	v_fmamk_f32 v99, v211, 0x3a800000, v232
	v_rsq_f32_e32 v106, v99
	s_nop 0
	v_pk_mul_f32 v[96:97], v[96:97], v[106:107] op_sel_hi:[1,0]
	v_pk_mul_f32 v[94:95], v[94:95], v[106:107] op_sel_hi:[1,0]
	v_mul_f32_e32 v100, v97, v97
	v_mul_f32_e32 v99, v95, v95
	v_fmac_f32_e32 v99, v94, v94
	v_fmac_f32_e32 v100, v96, v96
	v_add_f32_e32 v99, v99, v100
	v_pk_mul_f32 v[100:101], v[92:93], v[106:107] op_sel_hi:[1,0]
	v_pk_mul_f32 v[102:103], v[90:91], v[106:107] op_sel_hi:[1,0]
	v_mul_f32_e32 v91, v101, v101
	v_mul_f32_e32 v90, v103, v103
	v_fmac_f32_e32 v90, v102, v102
	v_fmac_f32_e32 v91, v100, v100
	v_add_f32_e32 v90, v90, v91
	v_add_f32_e32 v99, v99, v90
	v_pk_mul_f32 v[90:91], v[88:89], v[106:107] op_sel_hi:[1,0]
	v_pk_mul_f32 v[92:93], v[86:87], v[106:107] op_sel_hi:[1,0]
	v_mul_f32_e32 v87, v91, v91
	v_mul_f32_e32 v86, v93, v93
	v_pk_mul_f32 v[104:105], v[84:85], v[106:107] op_sel_hi:[1,0]
	v_pk_mul_f32 v[106:107], v[82:83], v[106:107] op_sel_hi:[1,0]
	v_fmac_f32_e32 v86, v92, v92
	v_fmac_f32_e32 v87, v90, v90
	v_mul_f32_e32 v82, v107, v107
	v_mul_f32_e32 v83, v105, v105
	v_add_f32_e32 v86, v86, v87
	v_fmac_f32_e32 v82, v106, v106
	v_fmac_f32_e32 v83, v104, v104
	v_add_f32_e32 v86, v86, v99
	v_add_f32_e32 v82, v82, v83
	v_add_f32_e32 v82, v82, v86
	ds_bpermute_b32 v83, v165, v82
	s_waitcnt lgkmcnt(0)
	v_add_f32_e32 v82, v82, v83
	ds_bpermute_b32 v83, v209, v82
	s_cbranch_vccnz .LBB0_337
	s_movk_i32 s22, 0x7fff
	v_cmp_lt_i32_e32 vcc, s22, v98
	s_and_saveexec_b64 s[22:23], vcc
	s_xor_b64 s[22:23], exec, s[22:23]
	v_add_u32_e32 v84, 0xffff8020, v164
	v_mov_b32_e32 v85, v0
	v_lshlrev_b64 v[84:85], 12, v[84:85]
	v_lshl_add_u64 v[84:85], s[10:11], 0, v[84:85]
	s_lshl_b32 s72, s17, 2
	v_lshl_add_u64 v[84:85], v[84:85], 0, s[72:73]
	v_mov_b32_e32 v161, v0
	v_lshl_add_u64 v[108:109], v[84:85], 0, v[160:161]
	s_andn2_saveexec_b64 s[22:23], s[22:23]
	s_cbranch_execz .LBB0_336
	v_and_b32_e32 v86, 0x3fef, v98
	v_add_u32_e32 v84, s38, v86
	v_ashrrev_i32_e32 v85, 31, v84
	v_lshlrev_b64 v[84:85], 12, v[84:85]
	v_lshl_add_u64 v[84:85], s[8:9], 0, v[84:85]
	s_lshl_b32 s72, s17, 2
	v_lshl_add_u64 v[84:85], v[84:85], 0, s[72:73]
	v_mov_b32_e32 v161, v0
	s_movk_i32 s24, 0x3dff
	v_lshl_add_u64 v[84:85], v[84:85], 0, v[160:161]
	v_cmp_lt_u32_e32 vcc, s24, v86
	s_nop 1
	v_cndmask_b32_e32 v109, 0, v85, vcc
	v_cndmask_b32_e32 v108, 0, v84, vcc

; __device__ __forceinline__ float rs_from_ss(float ss) { return __builtin_amdgcn_rsqf(ss * (1.0f / 1024.0f) + RMS_EPS); }
;     __device__ __forceinline__ void operator()(const f32x4 (&acc)[2][2][4][2], const Unit& u, int wr, int wc, int fr, int fq) const {
;     ...
;             for (int m = 0; m < 4; ++m) { const int row = row0 + ai * HALF + m * 16; const float rs = rs_from_ss(ss[row]); f32x4 v[2][2]; float sq = 0.f;
; #pragma unroll
;                 for (int bj = 0; bj < 2; ++bj)
; #pragma unroll
;                     for (int n = 0; n < 2; ++n) { v[bj][n] = acc[ai][bj][m][n] * rs; sq += (v[bj][n][0] * v[bj][n][0] + v[bj][n][1] * v[bj][n][1]) + (v[bj][n][2] * v[bj][n][2] + v[bj][n][3] * v[bj][n][3]); }
;                 sq += __shfl_xor(sq, 16); sq += __shfl_xor(sq, 32);
;                 const float rn = __builtin_amdgcn_rsqf(sq * (1.0f / 64.0f) + RMS_EPS);
;                 float* kd = nullptr;
;                 if (isK) { if (row < NP) { const int pos = row & 16383, b = row >> 14; if (pos >= 15872) kd = kp + ((size_t)(b * 512 + pos - 15872)) * 1024 + head * 64 + 8 * fq; }
;                            else kd = ks + (size_t)(row - NP) * 1024 + head * 64 + 8 * fq; }
.LBB0_341:
	s_or_b64 exec, exec, s[22:23]
	v_or_b32_e32 v82, 48, v164
	v_ashrrev_i32_e32 v83, 31, v82
	v_lshl_add_u64 v[84:85], v[82:83], 2, s[4:5]
	v_mov_b64_e32 v[92:93], 0
	s_and_b64 vcc, exec, s[46:47]
	v_fmamk_f32 v83, v212, 0x3a800000, v232
	v_rsq_f32_e32 v90, v83
	s_nop 0
	v_pk_mul_f32 v[80:81], v[80:81], v[90:91] op_sel_hi:[1,0]
	v_pk_mul_f32 v[78:79], v[78:79], v[90:91] op_sel_hi:[1,0]
	v_mul_f32_e32 v84, v81, v81
	v_mul_f32_e32 v83, v79, v79
	v_fmac_f32_e32 v83, v78, v78
	v_fmac_f32_e32 v84, v80, v80
	v_add_f32_e32 v83, v83, v84
	v_pk_mul_f32 v[84:85], v[76:77], v[90:91] op_sel_hi:[1,0]
	v_pk_mul_f32 v[86:87], v[74:75], v[90:91] op_sel_hi:[1,0]
	v_mul_f32_e32 v75, v85, v85
	v_mul_f32_e32 v74, v87, v87
	v_fmac_f32_e32 v74, v86, v86
	v_fmac_f32_e32 v75, v84, v84
	v_add_f32_e32 v74, v74, v75
	v_add_f32_e32 v83, v83, v74
	v_pk_mul_f32 v[74:75], v[72:73], v[90:91] op_sel_hi:[1,0]
	v_pk_mul_f32 v[76:77], v[70:71], v[90:91] op_sel_hi:[1,0]
	v_mul_f32_e32 v71, v75, v75
	v_mul_f32_e32 v70, v77, v77
	v_pk_mul_f32 v[88:89], v[68:69], v[90:91] op_sel_hi:[1,0]
	v_pk_mul_f32 v[90:91], v[66:67], v[90:91] op_sel_hi:[1,0]
	v_fmac_f32_e32 v70, v76, v76
	v_fmac_f32_e32 v71, v74, v74
	v_mul_f32_e32 v66, v91, v91
	v_mul_f32_e32 v67, v89, v89
	v_add_f32_e32 v70, v70, v71
	v_fmac_f32_e32 v66, v90, v90
	v_fmac_f32_e32 v67, v88, v88
	v_add_f32_e32 v70, v70, v83
	v_add_f32_e32 v66, v66, v67
	v_add_f32_e32 v66, v66, v70
	ds_bpermute_b32 v67, v165, v66
	s_waitcnt lgkmcnt(0)
	v_add_f32_e32 v66, v66, v67
	ds_bpermute_b32 v67, v209, v66
	s_cbranch_vccnz .LBB0_347
	s_movk_i32 s22, 0x7fff
	v_cmp_lt_i32_e32 vcc, s22, v82
	s_and_saveexec_b64 s[22:23], vcc
	s_xor_b64 s[22:23], exec, s[22:23]
	v_add_u32_e32 v68, 0xffff8030, v164
	v_mov_b32_e32 v69, v0
	v_lshlrev_b64 v[68:69], 12, v[68:69]
	v_lshl_add_u64 v[68:69], s[10:11], 0, v[68:69]
	s_lshl_b32 s72, s17, 2
	v_lshl_add_u64 v[68:69], v[68:69], 0, s[72:73]
	v_mov_b32_e32 v161, v0
	v_lshl_add_u64 v[92:93], v[68:69], 0, v[160:161]
	s_andn2_saveexec_b64 s[22:23], s[22:23]
	s_cbranch_execz .LBB0_346
	v_and_b32_e32 v70, 0x3fff, v82
	v_add_u32_e32 v68, s38, v70
	v_ashrrev_i32_e32 v69, 31, v68
	v_lshlrev_b64 v[68:69], 12, v[68:69]
	v_lshl_add_u64 v[68:69], s[8:9], 0, v[68:69]
	s_lshl_b32 s72, s17, 2
	v_lshl_add_u64 v[68:69], v[68:69], 0, s[72:73]
	v_mov_b32_e32 v161, v0
	s_movk_i32 s24, 0x3dff
	v_lshl_add_u64 v[68:69], v[68:69], 0, v[160:161]
	v_cmp_lt_u32_e32 vcc, s24, v70
	s_nop 1
	v_cndmask_b32_e32 v93, 0, v69, vcc
	v_cndmask_b32_e32 v92, 0, v68, vcc

; __device__ __forceinline__ float rs_from_ss(float ss) { return __builtin_amdgcn_rsqf(ss * (1.0f / 1024.0f) + RMS_EPS); }
;     __device__ __forceinline__ void operator()(const f32x4 (&acc)[2][2][4][2], const Unit& u, int wr, int wc, int fr, int fq) const {
;     ...
;             for (int m = 0; m < 4; ++m) { const int row = row0 + ai * HALF + m * 16; const float rs = rs_from_ss(ss[row]); f32x4 v[2][2]; float sq = 0.f;
; #pragma unroll
;                 for (int bj = 0; bj < 2; ++bj)
; #pragma unroll
;                     for (int n = 0; n < 2; ++n) { v[bj][n] = acc[ai][bj][m][n] * rs; sq += (v[bj][n][0] * v[bj][n][0] + v[bj][n][1] * v[bj][n][1]) + (v[bj][n][2] * v[bj][n][2] + v[bj][n][3] * v[bj][n][3]); }
;                 sq += __shfl_xor(sq, 16); sq += __shfl_xor(sq, 32);
;                 const float rn = __builtin_amdgcn_rsqf(sq * (1.0f / 64.0f) + RMS_EPS);
;                 float* kd = nullptr;
;                 if (isK) { if (row < NP) { const int pos = row & 16383, b = row >> 14; if (pos >= 15872) kd = kp + ((size_t)(b * 512 + pos - 15872)) * 1024 + head * 64 + 8 * fq; }
;                            else kd = ks + (size_t)(row - NP) * 1024 + head * 64 + 8 * fq; }
.LBB0_351:
	s_or_b64 exec, exec, s[22:23]
	v_add_u32_e32 v77, 0x80, v164
	v_ashrrev_i32_e32 v66, 5, v77
	v_and_b32_e32 v66, 0xfffffe00, v66
	v_add_u32_e32 v78, 0xffffc200, v66
	v_mov_b64_e32 v[74:75], 0
	s_and_b64 vcc, exec, s[46:47]
	v_fmamk_f32 v66, v213, 0x3a800000, v232
	v_rsq_f32_e32 v72, v66
	s_nop 0
	v_pk_mul_f32 v[64:65], v[64:65], v[72:73] op_sel_hi:[1,0]
	v_pk_mul_f32 v[62:63], v[62:63], v[72:73] op_sel_hi:[1,0]
	v_mul_f32_e32 v67, v65, v65
	v_mul_f32_e32 v66, v63, v63
	v_fmac_f32_e32 v66, v62, v62
	v_fmac_f32_e32 v67, v64, v64
	v_add_f32_e32 v70, v66, v67
	v_pk_mul_f32 v[66:67], v[60:61], v[72:73] op_sel_hi:[1,0]
	v_pk_mul_f32 v[68:69], v[58:59], v[72:73] op_sel_hi:[1,0]
	v_mul_f32_e32 v59, v67, v67
	v_mul_f32_e32 v58, v69, v69
	v_fmac_f32_e32 v58, v68, v68
	v_fmac_f32_e32 v59, v66, v66
	v_add_f32_e32 v58, v58, v59
	v_add_f32_e32 v70, v70, v58
	v_pk_mul_f32 v[58:59], v[56:57], v[72:73] op_sel_hi:[1,0]
	v_pk_mul_f32 v[60:61], v[54:55], v[72:73] op_sel_hi:[1,0]
	v_mul_f32_e32 v55, v59, v59
	v_mul_f32_e32 v54, v61, v61
	v_fmac_f32_e32 v54, v60, v60
	v_fmac_f32_e32 v55, v58, v58
	v_add_f32_e32 v54, v54, v55
	v_add_f32_e32 v54, v54, v70
	v_pk_mul_f32 v[70:71], v[52:53], v[72:73] op_sel_hi:[1,0]
	v_pk_mul_f32 v[72:73], v[50:51], v[72:73] op_sel_hi:[1,0]
	v_mul_f32_e32 v51, v71, v71
	v_mul_f32_e32 v50, v73, v73
	v_fmac_f32_e32 v50, v72, v72
	v_fmac_f32_e32 v51, v70, v70
	v_add_f32_e32 v50, v50, v51
	v_add_f32_e32 v50, v50, v54
	ds_bpermute_b32 v51, v165, v50
	s_waitcnt lgkmcnt(0)
	v_add_f32_e32 v50, v50, v51
	ds_bpermute_b32 v51, v209, v50
	s_cbranch_vccnz .LBB0_357
	s_movk_i32 s22, 0x7f7f
	v_cmp_lt_i32_e32 vcc, s22, v164
	s_and_saveexec_b64 s[22:23], vcc
	s_xor_b64 s[22:23], exec, s[22:23]
	v_add_u32_e32 v52, 0xffff8080, v164
	v_mov_b32_e32 v53, v0
	v_lshlrev_b64 v[52:53], 12, v[52:53]
	v_lshl_add_u64 v[52:53], s[10:11], 0, v[52:53]
	s_lshl_b32 s72, s17, 2
	v_lshl_add_u64 v[52:53], v[52:53], 0, s[72:73]
	v_mov_b32_e32 v161, v0
	v_lshl_add_u64 v[74:75], v[52:53], 0, v[160:161]
	s_andn2_saveexec_b64 s[22:23], s[22:23]
	s_cbranch_execz .LBB0_356
	v_and_b32_e32 v54, 0x3fcf, v77
	v_add_u32_e32 v52, v78, v54
	v_ashrrev_i32_e32 v53, 31, v52
	v_lshlrev_b64 v[52:53], 12, v[52:53]
	v_lshl_add_u64 v[52:53], s[8:9], 0, v[52:53]
	s_lshl_b32 s72, s17, 2
	v_lshl_add_u64 v[52:53], v[52:53], 0, s[72:73]
	v_mov_b32_e32 v161, v0
	s_movk_i32 s24, 0x3dff
	v_lshl_add_u64 v[52:53], v[52:53], 0, v[160:161]
	v_cmp_lt_u32_e32 vcc, s24, v54
	s_nop 1
	v_cndmask_b32_e32 v75, 0, v53, vcc
	v_cndmask_b32_e32 v74, 0, v52, vcc

; __device__ __forceinline__ float rs_from_ss(float ss) { return __builtin_amdgcn_rsqf(ss * (1.0f / 1024.0f) + RMS_EPS); }
;     __device__ __forceinline__ void operator()(const f32x4 (&acc)[2][2][4][2], const Unit& u, int wr, int wc, int fr, int fq) const {
;     ...
;             for (int m = 0; m < 4; ++m) { const int row = row0 + ai * HALF + m * 16; const float rs = rs_from_ss(ss[row]); f32x4 v[2][2]; float sq = 0.f;
; #pragma unroll
;                 for (int bj = 0; bj < 2; ++bj)
; #pragma unroll
;                     for (int n = 0; n < 2; ++n) { v[bj][n] = acc[ai][bj][m][n] * rs; sq += (v[bj][n][0] * v[bj][n][0] + v[bj][n][1] * v[bj][n][1]) + (v[bj][n][2] * v[bj][n][2] + v[bj][n][3] * v[bj][n][3]); }
;                 sq += __shfl_xor(sq, 16); sq += __shfl_xor(sq, 32);
;                 const float rn = __builtin_amdgcn_rsqf(sq * (1.0f / 64.0f) + RMS_EPS);
;                 float* kd = nullptr;
;                 if (isK) { if (row < NP) { const int pos = row & 16383, b = row >> 14; if (pos >= 15872) kd = kp + ((size_t)(b * 512 + pos - 15872)) * 1024 + head * 64 + 8 * fq; }
;                            else kd = ks + (size_t)(row - NP) * 1024 + head * 64 + 8 * fq; }
.LBB0_361:
	s_or_b64 exec, exec, s[22:23]
	v_add_u32_e32 v61, 0x90, v164
	v_mov_b64_e32 v[58:59], 0
	s_and_b64 vcc, exec, s[46:47]
	v_fmamk_f32 v50, v214, 0x3a800000, v232
	v_rsq_f32_e32 v56, v50
	s_nop 0
	v_pk_mul_f32 v[48:49], v[48:49], v[56:57] op_sel_hi:[1,0]
	v_pk_mul_f32 v[46:47], v[46:47], v[56:57] op_sel_hi:[1,0]
	v_mul_f32_e32 v51, v49, v49
	v_mul_f32_e32 v50, v47, v47
	v_fmac_f32_e32 v50, v46, v46
	v_fmac_f32_e32 v51, v48, v48
	v_add_f32_e32 v54, v50, v51
	v_pk_mul_f32 v[50:51], v[44:45], v[56:57] op_sel_hi:[1,0]
	v_pk_mul_f32 v[52:53], v[42:43], v[56:57] op_sel_hi:[1,0]
	v_mul_f32_e32 v43, v51, v51
	v_mul_f32_e32 v42, v53, v53
	v_fmac_f32_e32 v42, v52, v52
	v_fmac_f32_e32 v43, v50, v50
	v_add_f32_e32 v42, v42, v43
	v_add_f32_e32 v54, v54, v42
	v_pk_mul_f32 v[42:43], v[40:41], v[56:57] op_sel_hi:[1,0]
	v_pk_mul_f32 v[44:45], v[38:39], v[56:57] op_sel_hi:[1,0]
	v_mul_f32_e32 v39, v43, v43
	v_mul_f32_e32 v38, v45, v45
	v_fmac_f32_e32 v38, v44, v44
	v_fmac_f32_e32 v39, v42, v42
	v_add_f32_e32 v38, v38, v39
	v_add_f32_e32 v38, v38, v54
	v_pk_mul_f32 v[54:55], v[36:37], v[56:57] op_sel_hi:[1,0]
	v_pk_mul_f32 v[56:57], v[34:35], v[56:57] op_sel_hi:[1,0]
	v_mul_f32_e32 v35, v55, v55
	v_mul_f32_e32 v34, v57, v57
	v_fmac_f32_e32 v34, v56, v56
	v_fmac_f32_e32 v35, v54, v54
	v_add_f32_e32 v34, v34, v35
	v_add_f32_e32 v34, v34, v38
	ds_bpermute_b32 v35, v165, v34
	s_waitcnt lgkmcnt(0)
	v_add_f32_e32 v34, v34, v35
	ds_bpermute_b32 v35, v209, v34
	s_cbranch_vccnz .LBB0_367
	s_movk_i32 s22, 0x7f6f
	v_cmp_lt_i32_e32 vcc, s22, v164
	s_and_saveexec_b64 s[22:23], vcc
	s_xor_b64 s[22:23], exec, s[22:23]
	v_add_u32_e32 v36, 0xffff8090, v164
	v_mov_b32_e32 v37, v0
	v_lshlrev_b64 v[36:37], 12, v[36:37]
	v_lshl_add_u64 v[36:37], s[10:11], 0, v[36:37]
	s_lshl_b32 s72, s17, 2
	v_lshl_add_u64 v[36:37], v[36:37], 0, s[72:73]
	v_mov_b32_e32 v161, v0
	v_lshl_add_u64 v[58:59], v[36:37], 0, v[160:161]
	s_andn2_saveexec_b64 s[22:23], s[22:23]
	s_cbranch_execz .LBB0_366
	v_and_b32_e32 v38, 0x3fdf, v61
	v_add_u32_e32 v36, v78, v38
	v_ashrrev_i32_e32 v37, 31, v36
	v_lshlrev_b64 v[36:37], 12, v[36:37]
	v_lshl_add_u64 v[36:37], s[8:9], 0, v[36:37]
	s_lshl_b32 s72, s17, 2
	v_lshl_add_u64 v[36:37], v[36:37], 0, s[72:73]
	v_mov_b32_e32 v161, v0
	s_movk_i32 s24, 0x3dff
	v_lshl_add_u64 v[36:37], v[36:37], 0, v[160:161]
	v_cmp_lt_u32_e32 vcc, s24, v38
	s_nop 1
	v_cndmask_b32_e32 v59, 0, v37, vcc
	v_cndmask_b32_e32 v58, 0, v36, vcc

; __device__ __forceinline__ float rs_from_ss(float ss) { return __builtin_amdgcn_rsqf(ss * (1.0f / 1024.0f) + RMS_EPS); }
;     __device__ __forceinline__ void operator()(const f32x4 (&acc)[2][2][4][2], const Unit& u, int wr, int wc, int fr, int fq) const {
;     ...
;             for (int m = 0; m < 4; ++m) { const int row = row0 + ai * HALF + m * 16; const float rs = rs_from_ss(ss[row]); f32x4 v[2][2]; float sq = 0.f;
; #pragma unroll
;                 for (int bj = 0; bj < 2; ++bj)
; #pragma unroll
;                     for (int n = 0; n < 2; ++n) { v[bj][n] = acc[ai][bj][m][n] * rs; sq += (v[bj][n][0] * v[bj][n][0] + v[bj][n][1] * v[bj][n][1]) + (v[bj][n][2] * v[bj][n][2] + v[bj][n][3] * v[bj][n][3]); }
;                 sq += __shfl_xor(sq, 16); sq += __shfl_xor(sq, 32);
;                 const float rn = __builtin_amdgcn_rsqf(sq * (1.0f / 64.0f) + RMS_EPS);
;                 float* kd = nullptr;
;                 if (isK) { if (row < NP) { const int pos = row & 16383, b = row >> 14; if (pos >= 15872) kd = kp + ((size_t)(b * 512 + pos - 15872)) * 1024 + head * 64 + 8 * fq; }
;                            else kd = ks + (size_t)(row - NP) * 1024 + head * 64 + 8 * fq; }
.LBB0_371:
	s_or_b64 exec, exec, s[22:23]
	v_add_u32_e32 v45, 0xa0, v164
	v_mov_b64_e32 v[42:43], 0
	s_and_b64 vcc, exec, s[46:47]
	v_fmamk_f32 v34, v215, 0x3a800000, v232
	v_rsq_f32_e32 v40, v34
	s_nop 0
	v_pk_mul_f32 v[32:33], v[32:33], v[40:41] op_sel_hi:[1,0]
	v_pk_mul_f32 v[30:31], v[30:31], v[40:41] op_sel_hi:[1,0]
	v_mul_f32_e32 v35, v33, v33
	v_mul_f32_e32 v34, v31, v31
	v_fmac_f32_e32 v34, v30, v30
	v_fmac_f32_e32 v35, v32, v32
	v_add_f32_e32 v38, v34, v35
	v_pk_mul_f32 v[34:35], v[28:29], v[40:41] op_sel_hi:[1,0]
	v_pk_mul_f32 v[36:37], v[26:27], v[40:41] op_sel_hi:[1,0]
	v_mul_f32_e32 v27, v35, v35
	v_mul_f32_e32 v26, v37, v37
	v_fmac_f32_e32 v26, v36, v36
	v_fmac_f32_e32 v27, v34, v34
	v_add_f32_e32 v26, v26, v27
	v_add_f32_e32 v38, v38, v26
	v_pk_mul_f32 v[26:27], v[24:25], v[40:41] op_sel_hi:[1,0]
	v_pk_mul_f32 v[28:29], v[22:23], v[40:41] op_sel_hi:[1,0]
	v_mul_f32_e32 v23, v27, v27
	v_mul_f32_e32 v22, v29, v29
	v_fmac_f32_e32 v22, v28, v28
	v_fmac_f32_e32 v23, v26, v26
	v_add_f32_e32 v22, v22, v23
	v_add_f32_e32 v22, v22, v38
	v_pk_mul_f32 v[38:39], v[20:21], v[40:41] op_sel_hi:[1,0]
	v_pk_mul_f32 v[40:41], v[18:19], v[40:41] op_sel_hi:[1,0]
	v_mul_f32_e32 v19, v39, v39
	v_mul_f32_e32 v18, v41, v41
	v_fmac_f32_e32 v18, v40, v40
	v_fmac_f32_e32 v19, v38, v38
	v_add_f32_e32 v18, v18, v19
	v_add_f32_e32 v18, v18, v22
	ds_bpermute_b32 v19, v165, v18
	s_waitcnt lgkmcnt(0)
	v_add_f32_e32 v18, v18, v19
	ds_bpermute_b32 v19, v209, v18
	s_cbranch_vccnz .LBB0_377
	s_movk_i32 s22, 0x7f5f
	v_cmp_lt_i32_e32 vcc, s22, v164
	s_and_saveexec_b64 s[22:23], vcc
	s_xor_b64 s[22:23], exec, s[22:23]
	v_add_u32_e32 v20, 0xffff80a0, v164
	v_mov_b32_e32 v21, v0
	v_lshlrev_b64 v[20:21], 12, v[20:21]
	v_lshl_add_u64 v[20:21], s[10:11], 0, v[20:21]
	s_lshl_b32 s72, s17, 2
	v_lshl_add_u64 v[20:21], v[20:21], 0, s[72:73]
	v_mov_b32_e32 v161, v0
	v_lshl_add_u64 v[42:43], v[20:21], 0, v[160:161]
	s_andn2_saveexec_b64 s[22:23], s[22:23]
	s_cbranch_execz .LBB0_376
	v_and_b32_e32 v22, 0x3fef, v45
	v_add_u32_e32 v20, v78, v22
	v_ashrrev_i32_e32 v21, 31, v20
	v_lshlrev_b64 v[20:21], 12, v[20:21]
	v_lshl_add_u64 v[20:21], s[8:9], 0, v[20:21]
	s_lshl_b32 s72, s17, 2
	v_lshl_add_u64 v[20:21], v[20:21], 0, s[72:73]
	v_mov_b32_e32 v161, v0
	s_movk_i32 s24, 0x3dff
	v_lshl_add_u64 v[20:21], v[20:21], 0, v[160:161]
	v_cmp_lt_u32_e32 vcc, s24, v22
	s_nop 1
	v_cndmask_b32_e32 v43, 0, v21, vcc
	v_cndmask_b32_e32 v42, 0, v20, vcc

; __device__ __forceinline__ float rs_from_ss(float ss) { return __builtin_amdgcn_rsqf(ss * (1.0f / 1024.0f) + RMS_EPS); }
;     __device__ __forceinline__ void operator()(const f32x4 (&acc)[2][2][4][2], const Unit& u, int wr, int wc, int fr, int fq) const {
;     ...
;             for (int m = 0; m < 4; ++m) { const int row = row0 + ai * HALF + m * 16; const float rs = rs_from_ss(ss[row]); f32x4 v[2][2]; float sq = 0.f;
; #pragma unroll
;                 for (int bj = 0; bj < 2; ++bj)
; #pragma unroll
;                     for (int n = 0; n < 2; ++n) { v[bj][n] = acc[ai][bj][m][n] * rs; sq += (v[bj][n][0] * v[bj][n][0] + v[bj][n][1] * v[bj][n][1]) + (v[bj][n][2] * v[bj][n][2] + v[bj][n][3] * v[bj][n][3]); }
;                 sq += __shfl_xor(sq, 16); sq += __shfl_xor(sq, 32);
;                 const float rn = __builtin_amdgcn_rsqf(sq * (1.0f / 64.0f) + RMS_EPS);
;                 float* kd = nullptr;
;                 if (isK) { if (row < NP) { const int pos = row & 16383, b = row >> 14; if (pos >= 15872) kd = kp + ((size_t)(b * 512 + pos - 15872)) * 1024 + head * 64 + 8 * fq; }
;                            else kd = ks + (size_t)(row - NP) * 1024 + head * 64 + 8 * fq; }
.LBB0_381:
	s_or_b64 exec, exec, s[22:23]
	v_add_u32_e32 v29, 0xb0, v164
	v_mov_b64_e32 v[26:27], 0
	s_and_b64 vcc, exec, s[46:47]
	v_fmamk_f32 v18, v216, 0x3a800000, v232
	v_rsq_f32_e32 v24, v18
	s_nop 0
	v_pk_mul_f32 v[16:17], v[16:17], v[24:25] op_sel_hi:[1,0]
	v_pk_mul_f32 v[14:15], v[14:15], v[24:25] op_sel_hi:[1,0]
	v_mul_f32_e32 v19, v17, v17
	v_mul_f32_e32 v18, v15, v15
	v_fmac_f32_e32 v18, v14, v14
	v_fmac_f32_e32 v19, v16, v16
	v_add_f32_e32 v22, v18, v19
	v_pk_mul_f32 v[18:19], v[12:13], v[24:25] op_sel_hi:[1,0]
	v_pk_mul_f32 v[20:21], v[10:11], v[24:25] op_sel_hi:[1,0]
	v_mul_f32_e32 v11, v19, v19
	v_mul_f32_e32 v10, v21, v21
	v_fmac_f32_e32 v10, v20, v20
	v_fmac_f32_e32 v11, v18, v18
	v_add_f32_e32 v10, v10, v11
	v_add_f32_e32 v22, v22, v10
	v_pk_mul_f32 v[10:11], v[8:9], v[24:25] op_sel_hi:[1,0]
	v_pk_mul_f32 v[12:13], v[6:7], v[24:25] op_sel_hi:[1,0]
	v_mul_f32_e32 v7, v11, v11
	v_mul_f32_e32 v6, v13, v13
	v_fmac_f32_e32 v6, v12, v12
	v_fmac_f32_e32 v7, v10, v10
	v_add_f32_e32 v6, v6, v7
	v_add_f32_e32 v6, v6, v22
	v_pk_mul_f32 v[22:23], v[4:5], v[24:25] op_sel_hi:[1,0]
	v_pk_mul_f32 v[24:25], v[2:3], v[24:25] op_sel_hi:[1,0]
	v_mul_f32_e32 v3, v23, v23
	v_mul_f32_e32 v2, v25, v25
	v_fmac_f32_e32 v2, v24, v24
	v_fmac_f32_e32 v3, v22, v22
	v_add_f32_e32 v2, v2, v3
	v_add_f32_e32 v2, v2, v6
	ds_bpermute_b32 v3, v165, v2
	s_waitcnt lgkmcnt(0)
	v_add_f32_e32 v2, v2, v3
	ds_bpermute_b32 v3, v209, v2
	s_cbranch_vccnz .LBB0_387
	s_movk_i32 s22, 0x7f4f
	v_cmp_lt_i32_e32 vcc, s22, v164
	s_and_saveexec_b64 s[22:23], vcc
	s_xor_b64 s[22:23], exec, s[22:23]
	v_add_u32_e32 v4, 0xffff80b0, v164
	v_mov_b32_e32 v5, v0
	v_lshlrev_b64 v[4:5], 12, v[4:5]
	v_lshl_add_u64 v[4:5], s[10:11], 0, v[4:5]
	s_lshl_b32 s72, s17, 2
	v_lshl_add_u64 v[4:5], v[4:5], 0, s[72:73]
	v_mov_b32_e32 v161, v0
	v_lshl_add_u64 v[26:27], v[4:5], 0, v[160:161]
	s_andn2_saveexec_b64 s[22:23], s[22:23]
	s_cbranch_execz .LBB0_386
	v_and_b32_e32 v6, 0x3fff, v29
	v_add_u32_e32 v4, v78, v6
	v_ashrrev_i32_e32 v5, 31, v4
	v_lshlrev_b64 v[4:5], 12, v[4:5]
	v_lshl_add_u64 v[4:5], s[8:9], 0, v[4:5]
	s_lshl_b32 s72, s17, 2
	v_lshl_add_u64 v[4:5], v[4:5], 0, s[72:73]
	v_mov_b32_e32 v161, v0
	s_movk_i32 s17, 0x3dff
	v_lshl_add_u64 v[4:5], v[4:5], 0, v[160:161]
	v_cmp_lt_u32_e32 vcc, s17, v6
	s_nop 1
	v_cndmask_b32_e32 v27, 0, v5, vcc
	v_cndmask_b32_e32 v26, 0, v4, vcc
